# pf4fu + P6 epilogue LDS tables moved out of the ring so the post-loop vmcnt(0) drain before the P6 epilogue loads is dropped
# baseline (speedup 1.0000x reference)
.LBB0_1012:
	s_or_b64 exec, exec, s[2:3]
	s_waitcnt lgkmcnt(0)
	s_barrier
	v_lshlrev_b32_e32 v130, 2, v216
	global_load_dwordx4 v[14:17], v130, s[78:79]
	global_load_dwordx4 v[10:13], v130, s[78:79] offset:64
	global_load_dwordx4 v[6:9], v130, s[78:79] offset:512
	global_load_dwordx4 v[2:5], v130, s[78:79] offset:576
	v_lshlrev_b64 v[166:167], 10, v[140:141]
	v_lshlrev_b64 v[140:141], 10, v[142:143]
	v_lshl_add_u32 v143, v210, 2, 0
	v_add_u32_e32 v178, 0x22000, v143
	v_lshlrev_b64 v[174:175], 10, v[138:139]
	v_lshlrev_b64 v[138:139], 10, v[144:145]
	ds_read2_b32 v[144:145], v178 offset1:16
	v_or_b32_e32 v142, v215, v214
	v_lshlrev_b64 v[170:171], 10, v[134:135]
	v_lshlrev_b64 v[134:135], 10, v[148:149]
	v_or_b32_e32 v148, v142, v213
	s_waitcnt lgkmcnt(1)
	v_or_b32_e32 v179, v168, v148
	s_waitcnt lgkmcnt(0)
	v_pk_mul_f32 v[126:127], v[126:127], v[144:145] op_sel_hi:[1,0]
	v_pk_mul_f32 v[128:129], v[128:129], v[144:145] op_sel_hi:[1,0]
	v_pk_mul_f32 v[122:123], v[122:123], v[144:145] op_sel_hi:[1,0]
	v_pk_mul_f32 v[124:125], v[124:125], v[144:145] op_sel_hi:[1,0]
	v_pk_mul_f32 v[118:119], v[118:119], v[144:145] op_sel_hi:[1,0]
	v_pk_mul_f32 v[120:121], v[120:121], v[144:145] op_sel_hi:[1,0]
	v_pk_mul_f32 v[114:115], v[114:115], v[144:145] op_sel_hi:[1,0]
	v_pk_mul_f32 v[116:117], v[116:117], v[144:145] op_sel_hi:[1,0]
	v_mov_b32_e32 v144, v145
	v_lshlrev_b64 v[172:173], 10, v[136:137]
	v_lshl_add_u64 v[142:143], v[170:171], 2, s[8:9]
	v_pk_mul_f32 v[110:111], v[110:111], v[144:145] op_sel_hi:[1,0]
	v_pk_mul_f32 v[112:113], v[112:113], v[144:145] op_sel_hi:[1,0]
	v_pk_mul_f32 v[106:107], v[106:107], v[144:145] op_sel_hi:[1,0]
	v_pk_mul_f32 v[108:109], v[108:109], v[144:145] op_sel_hi:[1,0]
	v_pk_mul_f32 v[148:149], v[102:103], v[144:145] op_sel_hi:[1,0]
	v_cmp_ne_u32_e32 vcc, 0, v179
	v_lshlrev_b64 v[136:137], 10, v[146:147]
	v_lshl_add_u64 v[146:147], v[172:173], 2, s[8:9]
	v_lshl_add_u64 v[142:143], v[142:143], 0, v[130:131]
	v_pk_mul_f32 v[168:169], v[104:105], v[144:145] op_sel_hi:[1,0]
	v_lshl_add_u64 v[146:147], v[146:147], 0, v[130:131]
	v_pk_mul_f32 v[98:99], v[98:99], v[144:145] op_sel_hi:[1,0]
	v_pk_mul_f32 v[100:101], v[100:101], v[144:145] op_sel_hi:[1,0]
	s_waitcnt vmcnt(3)
	v_pk_mul_f32 v[102:103], v[16:17], v[128:129]
	v_pk_mul_f32 v[126:127], v[14:15], v[126:127]
	s_waitcnt vmcnt(2)
	v_pk_mul_f32 v[122:123], v[10:11], v[122:123]
	v_pk_mul_f32 v[124:125], v[12:13], v[124:125]
	s_waitcnt vmcnt(1)
	v_pk_mul_f32 v[120:121], v[8:9], v[120:121]
	v_pk_mul_f32 v[118:119], v[6:7], v[118:119]
	s_waitcnt vmcnt(0)
	v_pk_mul_f32 v[116:117], v[4:5], v[116:117]
	v_pk_mul_f32 v[114:115], v[2:3], v[114:115]
	v_pk_mul_f32 v[128:129], v[16:17], v[112:113]
	v_pk_mul_f32 v[170:171], v[14:15], v[110:111]
	v_pk_mul_f32 v[172:173], v[12:13], v[108:109]
	v_pk_mul_f32 v[176:177], v[10:11], v[106:107]
	v_cndmask_b32_e32 v105, v103, v209, vcc
	v_cndmask_b32_e32 v104, v102, v209, vcc
	v_cndmask_b32_e32 v103, v127, v209, vcc
	v_cndmask_b32_e32 v102, v126, v209, vcc
	v_cndmask_b32_e32 v107, v123, v209, vcc
	v_cndmask_b32_e32 v106, v122, v209, vcc
	v_cndmask_b32_e32 v109, v125, v209, vcc
	v_cndmask_b32_e32 v108, v124, v209, vcc
	v_cndmask_b32_e32 v113, v121, v209, vcc
	v_cndmask_b32_e32 v112, v120, v209, vcc
	v_cndmask_b32_e32 v111, v119, v209, vcc
	v_cndmask_b32_e32 v110, v118, v209, vcc
	v_cndmask_b32_e32 v117, v117, v209, vcc
	v_cndmask_b32_e32 v116, v116, v209, vcc
	v_cndmask_b32_e32 v115, v115, v209, vcc
	v_cndmask_b32_e32 v114, v114, v209, vcc
	v_cndmask_b32_e32 v121, v129, v209, vcc
	v_cndmask_b32_e32 v120, v128, v209, vcc
	v_cndmask_b32_e32 v119, v171, v209, vcc
	v_cndmask_b32_e32 v118, v170, v209, vcc
	v_cndmask_b32_e32 v125, v173, v209, vcc
	v_cndmask_b32_e32 v124, v172, v209, vcc
	v_cndmask_b32_e32 v123, v177, v209, vcc
	v_cndmask_b32_e32 v122, v176, v209, vcc
	global_store_dwordx4 v[142:143], v[102:105], off
	global_store_dwordx4 v[142:143], v[106:109], off offset:64
	global_store_dwordx4 v[142:143], v[110:113], off offset:512
	global_store_dwordx4 v[142:143], v[114:117], off offset:576
	global_store_dwordx4 v[146:147], v[118:121], off
	global_store_dwordx4 v[146:147], v[122:125], off offset:64
	v_pk_mul_f32 v[102:103], v[8:9], v[168:169]
	v_pk_mul_f32 v[106:107], v[6:7], v[148:149]
	v_cndmask_b32_e32 v105, v103, v209, vcc
	v_cndmask_b32_e32 v104, v102, v209, vcc
	v_cndmask_b32_e32 v103, v107, v209, vcc
	v_cndmask_b32_e32 v102, v106, v209, vcc
	global_store_dwordx4 v[146:147], v[102:105], off offset:512
	ds_read2_b32 v[102:103], v178 offset0:32 offset1:48
	v_pk_mul_f32 v[100:101], v[4:5], v[100:101]
	v_pk_mul_f32 v[98:99], v[2:3], v[98:99]
	v_cndmask_b32_e32 v101, v101, v209, vcc
	v_cndmask_b32_e32 v100, v100, v209, vcc
	v_cndmask_b32_e32 v99, v99, v209, vcc
	v_cndmask_b32_e32 v98, v98, v209, vcc
	s_waitcnt lgkmcnt(0)
	v_pk_mul_f32 v[82:83], v[82:83], v[102:103] op_sel_hi:[1,0]
	v_pk_mul_f32 v[84:85], v[84:85], v[102:103] op_sel_hi:[1,0]
	global_store_dwordx4 v[146:147], v[98:101], off offset:576
	v_pk_mul_f32 v[84:85], v[4:5], v[84:85]
	v_pk_mul_f32 v[82:83], v[2:3], v[82:83]
	v_lshl_add_u64 v[98:99], v[174:175], 2, s[8:9]
	v_lshl_add_u64 v[98:99], v[98:99], 0, v[130:131]
	v_cndmask_b32_e32 v85, v85, v209, vcc
	v_cndmask_b32_e32 v84, v84, v209, vcc
	v_cndmask_b32_e32 v83, v83, v209, vcc
	v_cndmask_b32_e32 v82, v82, v209, vcc
	global_store_dwordx4 v[98:99], v[82:85], off offset:576
	v_pk_mul_f32 v[86:87], v[86:87], v[102:103] op_sel_hi:[1,0]
	v_pk_mul_f32 v[88:89], v[88:89], v[102:103] op_sel_hi:[1,0]
	v_mov_b32_e32 v82, v103
	v_pk_mul_f32 v[70:71], v[70:71], v[82:83] op_sel_hi:[1,0]
	v_pk_mul_f32 v[72:73], v[72:73], v[82:83] op_sel_hi:[1,0]
	v_lshl_add_u64 v[84:85], v[166:167], 2, s[8:9]
	v_pk_mul_f32 v[72:73], v[8:9], v[72:73]
	v_pk_mul_f32 v[70:71], v[6:7], v[70:71]
	v_lshl_add_u64 v[84:85], v[84:85], 0, v[130:131]
	v_cndmask_b32_e32 v73, v73, v209, vcc
	v_cndmask_b32_e32 v72, v72, v209, vcc
	v_cndmask_b32_e32 v71, v71, v209, vcc
	v_cndmask_b32_e32 v70, v70, v209, vcc
	global_store_dwordx4 v[84:85], v[70:73], off offset:512
	ds_read2_b32 v[70:71], v178 offset0:128 offset1:144
	v_pk_mul_f32 v[66:67], v[66:67], v[82:83] op_sel_hi:[1,0]
	v_pk_mul_f32 v[68:69], v[68:69], v[82:83] op_sel_hi:[1,0]
	v_pk_mul_f32 v[66:67], v[2:3], v[66:67]
	v_pk_mul_f32 v[68:69], v[4:5], v[68:69]
	v_cndmask_b32_e32 v67, v67, v209, vcc
	v_cndmask_b32_e32 v69, v69, v209, vcc
	v_cndmask_b32_e32 v68, v68, v209, vcc
	v_cndmask_b32_e32 v66, v66, v209, vcc
	s_waitcnt lgkmcnt(0)
	v_pk_mul_f32 v[50:51], v[50:51], v[70:71] op_sel_hi:[1,0]
	v_pk_mul_f32 v[52:53], v[52:53], v[70:71] op_sel_hi:[1,0]
	global_store_dwordx4 v[84:85], v[66:69], off offset:576
	v_pk_mul_f32 v[52:53], v[4:5], v[52:53]
	v_pk_mul_f32 v[50:51], v[2:3], v[50:51]
	v_lshl_add_u64 v[66:67], v[140:141], 2, s[8:9]
	v_lshl_add_u64 v[66:67], v[66:67], 0, v[130:131]
	v_cndmask_b32_e32 v53, v53, v209, vcc
	v_cndmask_b32_e32 v52, v52, v209, vcc
	v_cndmask_b32_e32 v51, v51, v209, vcc
	v_cndmask_b32_e32 v50, v50, v209, vcc
	global_store_dwordx4 v[66:67], v[50:53], off offset:576
	v_pk_mul_f32 v[88:89], v[8:9], v[88:89]
	v_pk_mul_f32 v[86:87], v[6:7], v[86:87]
	v_mov_b32_e32 v50, v71
	v_pk_mul_f32 v[38:39], v[38:39], v[50:51] op_sel_hi:[1,0]
	v_pk_mul_f32 v[40:41], v[40:41], v[50:51] op_sel_hi:[1,0]
	v_lshl_add_u64 v[52:53], v[138:139], 2, s[8:9]
	v_pk_mul_f32 v[40:41], v[8:9], v[40:41]
	v_pk_mul_f32 v[38:39], v[6:7], v[38:39]
	v_lshl_add_u64 v[52:53], v[52:53], 0, v[130:131]
	v_cndmask_b32_e32 v41, v41, v209, vcc
	v_cndmask_b32_e32 v40, v40, v209, vcc
	v_cndmask_b32_e32 v39, v39, v209, vcc
	v_cndmask_b32_e32 v38, v38, v209, vcc
	global_store_dwordx4 v[52:53], v[38:41], off offset:512
	ds_read2_b32 v[38:39], v178 offset0:160 offset1:176
	v_pk_mul_f32 v[34:35], v[34:35], v[50:51] op_sel_hi:[1,0]
	v_pk_mul_f32 v[36:37], v[36:37], v[50:51] op_sel_hi:[1,0]
	v_pk_mul_f32 v[34:35], v[2:3], v[34:35]
	v_pk_mul_f32 v[36:37], v[4:5], v[36:37]
	v_cndmask_b32_e32 v35, v35, v209, vcc
	v_cndmask_b32_e32 v37, v37, v209, vcc
	v_cndmask_b32_e32 v36, v36, v209, vcc
	v_cndmask_b32_e32 v34, v34, v209, vcc
	s_waitcnt lgkmcnt(0)
	v_pk_mul_f32 v[18:19], v[18:19], v[38:39] op_sel_hi:[1,0]
	v_pk_mul_f32 v[20:21], v[20:21], v[38:39] op_sel_hi:[1,0]
	global_store_dwordx4 v[52:53], v[34:37], off offset:576
	v_pk_mul_f32 v[22:23], v[22:23], v[38:39] op_sel_hi:[1,0]
	v_pk_mul_f32 v[24:25], v[24:25], v[38:39] op_sel_hi:[1,0]
	v_lshl_add_u64 v[34:35], v[136:137], 2, s[8:9]
	v_pk_mul_f32 v[20:21], v[4:5], v[20:21]
	v_pk_mul_f32 v[18:19], v[2:3], v[18:19]
	v_lshl_add_u64 v[34:35], v[34:35], 0, v[130:131]
	v_pk_mul_f32 v[24:25], v[8:9], v[24:25]
	v_pk_mul_f32 v[22:23], v[6:7], v[22:23]
	v_cndmask_b32_e32 v21, v21, v209, vcc
	v_cndmask_b32_e32 v20, v20, v209, vcc
	v_cndmask_b32_e32 v19, v19, v209, vcc
	v_cndmask_b32_e32 v18, v18, v209, vcc
	v_cndmask_b32_e32 v89, v89, v209, vcc
	v_cndmask_b32_e32 v88, v88, v209, vcc
	v_cndmask_b32_e32 v87, v87, v209, vcc
	v_cndmask_b32_e32 v86, v86, v209, vcc
	v_cndmask_b32_e32 v25, v25, v209, vcc
	v_cndmask_b32_e32 v24, v24, v209, vcc
	v_cndmask_b32_e32 v23, v23, v209, vcc
	v_cndmask_b32_e32 v22, v22, v209, vcc
	global_store_dwordx4 v[34:35], v[18:21], off offset:576
	v_pk_mul_f32 v[94:95], v[94:95], v[102:103] op_sel_hi:[1,0]
	v_pk_mul_f32 v[96:97], v[96:97], v[102:103] op_sel_hi:[1,0]
	v_mov_b32_e32 v18, v39
	global_store_dwordx4 v[98:99], v[86:89], off offset:512
	v_pk_mul_f32 v[78:79], v[78:79], v[82:83] op_sel_hi:[1,0]
	v_pk_mul_f32 v[80:81], v[80:81], v[82:83] op_sel_hi:[1,0]
	v_pk_mul_f32 v[62:63], v[62:63], v[70:71] op_sel_hi:[1,0]
	v_pk_mul_f32 v[64:65], v[64:65], v[70:71] op_sel_hi:[1,0]
	v_pk_mul_f32 v[46:47], v[46:47], v[50:51] op_sel_hi:[1,0]
	v_pk_mul_f32 v[48:49], v[48:49], v[50:51] op_sel_hi:[1,0]
	v_pk_mul_f32 v[30:31], v[30:31], v[38:39] op_sel_hi:[1,0]
	v_pk_mul_f32 v[32:33], v[32:33], v[38:39] op_sel_hi:[1,0]
	global_store_dwordx4 v[34:35], v[22:25], off offset:512
	v_pk_mul_f32 v[20:21], v[164:165], v[18:19] op_sel_hi:[1,0]
	v_pk_mul_f32 v[96:97], v[16:17], v[96:97]
	v_pk_mul_f32 v[22:23], v[160:161], v[18:19] op_sel_hi:[1,0]
	v_pk_mul_f32 v[94:95], v[14:15], v[94:95]
	v_pk_mul_f32 v[80:81], v[16:17], v[80:81]
	v_pk_mul_f32 v[78:79], v[14:15], v[78:79]
	v_pk_mul_f32 v[64:65], v[16:17], v[64:65]
	v_pk_mul_f32 v[62:63], v[14:15], v[62:63]
	v_pk_mul_f32 v[48:49], v[16:17], v[48:49]
	v_pk_mul_f32 v[46:47], v[14:15], v[46:47]
	v_pk_mul_f32 v[32:33], v[16:17], v[32:33]
	v_pk_mul_f32 v[30:31], v[14:15], v[30:31]
	v_pk_mul_f32 v[16:17], v[16:17], v[22:23]
	v_pk_mul_f32 v[14:15], v[14:15], v[20:21]
	v_lshl_add_u64 v[20:21], v[134:135], 2, s[8:9]
	v_cndmask_b32_e32 v81, v81, v209, vcc
	v_cndmask_b32_e32 v80, v80, v209, vcc
	v_cndmask_b32_e32 v79, v79, v209, vcc
	v_cndmask_b32_e32 v78, v78, v209, vcc
	v_cndmask_b32_e32 v17, v17, v209, vcc
	v_cndmask_b32_e32 v16, v16, v209, vcc
	v_cndmask_b32_e32 v15, v15, v209, vcc
	v_cndmask_b32_e32 v14, v14, v209, vcc
	v_lshl_add_u64 v[20:21], v[20:21], 0, v[130:131]
	v_pk_mul_f32 v[90:91], v[90:91], v[102:103] op_sel_hi:[1,0]
	v_pk_mul_f32 v[92:93], v[92:93], v[102:103] op_sel_hi:[1,0]
	global_store_dwordx4 v[84:85], v[78:81], off
	v_pk_mul_f32 v[74:75], v[74:75], v[82:83] op_sel_hi:[1,0]
	v_pk_mul_f32 v[76:77], v[76:77], v[82:83] op_sel_hi:[1,0]
	v_pk_mul_f32 v[58:59], v[58:59], v[70:71] op_sel_hi:[1,0]
	v_pk_mul_f32 v[60:61], v[60:61], v[70:71] op_sel_hi:[1,0]
	v_pk_mul_f32 v[42:43], v[42:43], v[50:51] op_sel_hi:[1,0]
	v_pk_mul_f32 v[44:45], v[44:45], v[50:51] op_sel_hi:[1,0]
	v_pk_mul_f32 v[26:27], v[26:27], v[38:39] op_sel_hi:[1,0]
	v_pk_mul_f32 v[28:29], v[28:29], v[38:39] op_sel_hi:[1,0]
	global_store_dwordx4 v[20:21], v[14:17], off
	v_pk_mul_f32 v[92:93], v[12:13], v[92:93]
	v_pk_mul_f32 v[90:91], v[10:11], v[90:91]
	v_pk_mul_f32 v[14:15], v[162:163], v[18:19] op_sel_hi:[1,0]
	v_pk_mul_f32 v[16:17], v[154:155], v[18:19] op_sel_hi:[1,0]
	v_pk_mul_f32 v[76:77], v[12:13], v[76:77]
	v_pk_mul_f32 v[74:75], v[10:11], v[74:75]
	v_pk_mul_f32 v[60:61], v[12:13], v[60:61]
	v_pk_mul_f32 v[58:59], v[10:11], v[58:59]
	v_pk_mul_f32 v[44:45], v[12:13], v[44:45]
	v_pk_mul_f32 v[42:43], v[10:11], v[42:43]
	v_pk_mul_f32 v[28:29], v[12:13], v[28:29]
	v_pk_mul_f32 v[26:27], v[10:11], v[26:27]
	v_pk_mul_f32 v[12:13], v[12:13], v[16:17]
	v_pk_mul_f32 v[10:11], v[10:11], v[14:15]
	v_cndmask_b32_e32 v77, v77, v209, vcc
	v_cndmask_b32_e32 v76, v76, v209, vcc
	v_cndmask_b32_e32 v75, v75, v209, vcc
	v_cndmask_b32_e32 v74, v74, v209, vcc
	v_cndmask_b32_e32 v13, v13, v209, vcc
	v_cndmask_b32_e32 v12, v12, v209, vcc
	v_cndmask_b32_e32 v11, v11, v209, vcc
	v_cndmask_b32_e32 v10, v10, v209, vcc
	global_store_dwordx4 v[84:85], v[74:77], off offset:64
	v_pk_mul_f32 v[54:55], v[54:55], v[70:71] op_sel_hi:[1,0]
	v_pk_mul_f32 v[56:57], v[56:57], v[70:71] op_sel_hi:[1,0]
	global_store_dwordx4 v[20:21], v[10:13], off offset:64
	v_pk_mul_f32 v[56:57], v[8:9], v[56:57]
	v_pk_mul_f32 v[54:55], v[6:7], v[54:55]
	v_pk_mul_f32 v[10:11], v[158:159], v[18:19] op_sel_hi:[1,0]
	v_pk_mul_f32 v[12:13], v[152:153], v[18:19] op_sel_hi:[1,0]
	v_pk_mul_f32 v[6:7], v[6:7], v[10:11]
	v_pk_mul_f32 v[8:9], v[8:9], v[12:13]
	v_cndmask_b32_e32 v7, v7, v209, vcc
	v_cndmask_b32_e32 v9, v9, v209, vcc
	v_cndmask_b32_e32 v8, v8, v209, vcc
	v_cndmask_b32_e32 v6, v6, v209, vcc
	global_store_dwordx4 v[20:21], v[6:9], off offset:512
	v_cndmask_b32_e32 v97, v97, v209, vcc
	v_cndmask_b32_e32 v96, v96, v209, vcc
	v_pk_mul_f32 v[6:7], v[156:157], v[18:19] op_sel_hi:[1,0]
	v_pk_mul_f32 v[8:9], v[150:151], v[18:19] op_sel_hi:[1,0]
	v_pk_mul_f32 v[2:3], v[2:3], v[6:7]
	v_pk_mul_f32 v[4:5], v[4:5], v[8:9]
	v_cndmask_b32_e32 v95, v95, v209, vcc
	v_cndmask_b32_e32 v94, v94, v209, vcc
	v_cndmask_b32_e32 v93, v93, v209, vcc
	v_cndmask_b32_e32 v92, v92, v209, vcc
	v_cndmask_b32_e32 v91, v91, v209, vcc
	v_cndmask_b32_e32 v90, v90, v209, vcc
	v_cndmask_b32_e32 v65, v65, v209, vcc
	v_cndmask_b32_e32 v64, v64, v209, vcc
	v_cndmask_b32_e32 v63, v63, v209, vcc
	v_cndmask_b32_e32 v62, v62, v209, vcc
	v_cndmask_b32_e32 v61, v61, v209, vcc
	v_cndmask_b32_e32 v60, v60, v209, vcc
	v_cndmask_b32_e32 v59, v59, v209, vcc
	v_cndmask_b32_e32 v58, v58, v209, vcc
	v_cndmask_b32_e32 v57, v57, v209, vcc
	v_cndmask_b32_e32 v56, v56, v209, vcc
	v_cndmask_b32_e32 v55, v55, v209, vcc
	v_cndmask_b32_e32 v54, v54, v209, vcc
	v_cndmask_b32_e32 v49, v49, v209, vcc
	v_cndmask_b32_e32 v48, v48, v209, vcc
	v_cndmask_b32_e32 v47, v47, v209, vcc
	v_cndmask_b32_e32 v46, v46, v209, vcc
	v_cndmask_b32_e32 v45, v45, v209, vcc
	v_cndmask_b32_e32 v44, v44, v209, vcc
	v_cndmask_b32_e32 v43, v43, v209, vcc
	v_cndmask_b32_e32 v42, v42, v209, vcc
	v_cndmask_b32_e32 v33, v33, v209, vcc
	v_cndmask_b32_e32 v32, v32, v209, vcc
	v_cndmask_b32_e32 v31, v31, v209, vcc
	v_cndmask_b32_e32 v30, v30, v209, vcc
	v_cndmask_b32_e32 v29, v29, v209, vcc
	v_cndmask_b32_e32 v28, v28, v209, vcc
	v_cndmask_b32_e32 v27, v27, v209, vcc
	v_cndmask_b32_e32 v26, v26, v209, vcc
	v_cndmask_b32_e32 v5, v5, v209, vcc
	v_cndmask_b32_e32 v4, v4, v209, vcc
	v_cndmask_b32_e32 v3, v3, v209, vcc
	v_cndmask_b32_e32 v2, v2, v209, vcc
	global_store_dwordx4 v[98:99], v[94:97], off
	global_store_dwordx4 v[98:99], v[90:93], off offset:64
	global_store_dwordx4 v[66:67], v[62:65], off
	global_store_dwordx4 v[66:67], v[58:61], off offset:64
	global_store_dwordx4 v[66:67], v[54:57], off offset:512
	global_store_dwordx4 v[52:53], v[46:49], off
	global_store_dwordx4 v[52:53], v[42:45], off offset:64
	global_store_dwordx4 v[34:35], v[30:33], off
	global_store_dwordx4 v[34:35], v[26:29], off offset:64
	global_store_dwordx4 v[20:21], v[2:5], off offset:576

.LBB0_1018:
	s_add_u32 s4, s70, s56
	s_addc_u32 s5, s71, s57
	s_add_u32 s59, s70, s2
	s_addc_u32 s60, s71, s3
	s_add_i32 s61, 0, 0x10000
	s_cmp_eq_u32 s58, 40
	s_cselect_b32 s31, s1, s5
	s_cselect_b32 s30, s0, s4
	s_cselect_b32 s5, s15, s60
	s_cselect_b32 s4, s14, s59
	s_add_i32 s59, 0, 0x14000
	v_add_u32_e32 v154, s61, v140
	v_add_u32_e32 v170, s59, v140
	ds_read_b128 v[142:145], v154
	ds_read_b128 v[146:149], v154 offset:1024
	ds_read_b128 v[150:153], v154 offset:2048
	ds_read_b128 v[154:157], v154 offset:3072
	ds_read_b128 v[158:161], v170
	ds_read_b128 v[162:165], v170 offset:1024
	ds_read_b128 v[166:169], v170 offset:2048
	ds_read_b128 v[170:173], v170 offset:3072
	v_lshl_add_u64 v[214:215], s[70:71], 0, v[136:137]
	s_add_i32 m0, s50, 0xc000
	ds_read_b128 v[174:177], v141
	ds_read_b128 v[178:181], v141 offset:1024
	ds_read_b128 v[182:185], v141 offset:2048
	ds_read_b128 v[186:189], v141 offset:3072
	ds_read_b128 v[190:193], v141 offset:4096
	ds_read_b128 v[194:197], v141 offset:5120
	ds_read_b128 v[198:201], v141 offset:6144
	ds_read_b128 v[202:205], v141 offset:7168
	global_load_lds_dwordx4 v[214:215], off
	v_lshl_add_u64 v[214:215], s[70:71], 0, v[138:139]
	s_add_i32 m0, s50, 0xe000
	s_nop 0
	global_load_lds_dwordx4 v[214:215], off
	s_waitcnt vmcnt(8)
	s_waitcnt lgkmcnt(0)
	s_barrier
	s_setprio 1
	v_mfma_f32_16x16x32_bf16 v[126:129], v[142:145], v[174:177], v[126:129]
	v_mfma_f32_16x16x32_bf16 v[126:129], v[146:149], v[178:181], v[126:129]
	v_mfma_f32_16x16x32_bf16 v[122:125], v[150:153], v[174:177], v[122:125]
	v_mfma_f32_16x16x32_bf16 v[122:125], v[154:157], v[178:181], v[122:125]
	v_mfma_f32_16x16x32_bf16 v[106:109], v[150:153], v[182:185], v[106:109]
	v_mfma_f32_16x16x32_bf16 v[106:109], v[154:157], v[186:189], v[106:109]
	v_mfma_f32_16x16x32_bf16 v[110:113], v[142:145], v[182:185], v[110:113]
	v_mfma_f32_16x16x32_bf16 v[110:113], v[146:149], v[186:189], v[110:113]
	v_mfma_f32_16x16x32_bf16 v[94:97], v[142:145], v[190:193], v[94:97]
	v_mfma_f32_16x16x32_bf16 v[94:97], v[146:149], v[194:197], v[94:97]
	v_mfma_f32_16x16x32_bf16 v[90:93], v[150:153], v[190:193], v[90:93]
	v_mfma_f32_16x16x32_bf16 v[90:93], v[154:157], v[194:197], v[90:93]
	v_mfma_f32_16x16x32_bf16 v[74:77], v[150:153], v[198:201], v[74:77]
	v_mfma_f32_16x16x32_bf16 v[74:77], v[154:157], v[202:205], v[74:77]
	v_mfma_f32_16x16x32_bf16 v[78:81], v[142:145], v[198:201], v[78:81]
	v_mfma_f32_16x16x32_bf16 v[78:81], v[146:149], v[202:205], v[78:81]
	v_mfma_f32_16x16x32_bf16 v[118:121], v[158:161], v[174:177], v[118:121]
	v_mfma_f32_16x16x32_bf16 v[118:121], v[162:165], v[178:181], v[118:121]
	v_mfma_f32_16x16x32_bf16 v[114:117], v[166:169], v[174:177], v[114:117]
	v_mfma_f32_16x16x32_bf16 v[114:117], v[170:173], v[178:181], v[114:117]
	v_mfma_f32_16x16x32_bf16 v[98:101], v[166:169], v[182:185], v[98:101]
	v_mfma_f32_16x16x32_bf16 v[98:101], v[170:173], v[186:189], v[98:101]
	v_mfma_f32_16x16x32_bf16 v[102:105], v[158:161], v[182:185], v[102:105]
	v_mfma_f32_16x16x32_bf16 v[102:105], v[162:165], v[186:189], v[102:105]
	v_mfma_f32_16x16x32_bf16 v[86:89], v[158:161], v[190:193], v[86:89]
	v_mfma_f32_16x16x32_bf16 v[86:89], v[162:165], v[194:197], v[86:89]
	v_mfma_f32_16x16x32_bf16 v[82:85], v[166:169], v[190:193], v[82:85]
	v_mfma_f32_16x16x32_bf16 v[82:85], v[170:173], v[194:197], v[82:85]
	s_setprio 2
	s_barrier
	v_mfma_f32_16x16x32_bf16 v[66:69], v[166:169], v[198:201], v[66:69]
	v_mfma_f32_16x16x32_bf16 v[66:69], v[170:173], v[202:205], v[66:69]
	v_mfma_f32_16x16x32_bf16 v[70:73], v[158:161], v[198:201], v[70:73]
	v_mfma_f32_16x16x32_bf16 v[70:73], v[162:165], v[202:205], v[70:73]
	s_setprio 0
	s_nop 0
	s_add_i32 s60, s61, s39
	v_lshl_add_u64 v[214:215], s[4:5], 0, v[130:131]
	s_mov_b32 m0, s60
	ds_read_b128 v[174:177], v141 offset:16384
	ds_read_b128 v[178:181], v141 offset:17408
	ds_read_b128 v[182:185], v141 offset:18432
	ds_read_b128 v[186:189], v141 offset:19456
	ds_read_b128 v[190:193], v141 offset:20480
	ds_read_b128 v[194:197], v141 offset:21504
	ds_read_b128 v[198:201], v141 offset:22528
	ds_read_b128 v[202:205], v141 offset:23552
	global_load_lds_dwordx4 v[214:215], off
	s_add_i32 m0, s60, 0x2000
	s_add_u32 s60, s4, 0xb0000
	v_lshl_add_u64 v[216:217], s[4:5], 0, v[134:135]
	s_addc_u32 s61, s5, 0
	s_add_i32 s59, s59, s39
	global_load_lds_dwordx4 v[216:217], off
	v_lshl_add_u64 v[218:219], s[60:61], 0, v[130:131]
	s_mov_b32 m0, s59
	v_lshl_add_u64 v[220:221], s[30:31], 0, v[134:135]
	global_load_lds_dwordx4 v[218:219], off
	v_lshl_add_u64 v[218:219], s[60:61], 0, v[134:135]
	s_add_i32 m0, s59, 0x2000
	s_nop 0
	global_load_lds_dwordx4 v[218:219], off
	v_lshl_add_u64 v[218:219], s[30:31], 0, v[130:131]
	s_mov_b32 m0, s50
	s_nop 0
	global_load_lds_dwordx4 v[218:219], off
	s_mov_b32 m0, s51
	s_nop 0
	global_load_lds_dwordx4 v[220:221], off
	s_waitcnt vmcnt(8)
	s_waitcnt lgkmcnt(0)
	s_barrier
	s_setprio 1
	v_mfma_f32_16x16x32_bf16 v[62:65], v[142:145], v[174:177], v[62:65]
	v_mfma_f32_16x16x32_bf16 v[62:65], v[146:149], v[178:181], v[62:65]
	v_mfma_f32_16x16x32_bf16 v[58:61], v[150:153], v[174:177], v[58:61]
	v_mfma_f32_16x16x32_bf16 v[58:61], v[154:157], v[178:181], v[58:61]
	v_mfma_f32_16x16x32_bf16 v[42:45], v[150:153], v[182:185], v[42:45]
	v_mfma_f32_16x16x32_bf16 v[42:45], v[154:157], v[186:189], v[42:45]
	v_mfma_f32_16x16x32_bf16 v[46:49], v[142:145], v[182:185], v[46:49]
	v_mfma_f32_16x16x32_bf16 v[46:49], v[146:149], v[186:189], v[46:49]
	v_mfma_f32_16x16x32_bf16 v[30:33], v[142:145], v[190:193], v[30:33]
	v_mfma_f32_16x16x32_bf16 v[30:33], v[146:149], v[194:197], v[30:33]
	v_mfma_f32_16x16x32_bf16 v[26:29], v[150:153], v[190:193], v[26:29]
	v_mfma_f32_16x16x32_bf16 v[26:29], v[154:157], v[194:197], v[26:29]
	v_mfma_f32_16x16x32_bf16 v[10:13], v[150:153], v[198:201], v[10:13]
	v_mfma_f32_16x16x32_bf16 v[10:13], v[154:157], v[202:205], v[10:13]
	v_mfma_f32_16x16x32_bf16 v[14:17], v[142:145], v[198:201], v[14:17]
	v_mfma_f32_16x16x32_bf16 v[14:17], v[146:149], v[202:205], v[14:17]
	v_mfma_f32_16x16x32_bf16 v[54:57], v[158:161], v[174:177], v[54:57]
	v_mfma_f32_16x16x32_bf16 v[54:57], v[162:165], v[178:181], v[54:57]
	v_mfma_f32_16x16x32_bf16 v[50:53], v[166:169], v[174:177], v[50:53]
	v_mfma_f32_16x16x32_bf16 v[50:53], v[170:173], v[178:181], v[50:53]
	v_mfma_f32_16x16x32_bf16 v[34:37], v[166:169], v[182:185], v[34:37]
	v_mfma_f32_16x16x32_bf16 v[34:37], v[170:173], v[186:189], v[34:37]
	v_mfma_f32_16x16x32_bf16 v[38:41], v[158:161], v[182:185], v[38:41]
	v_mfma_f32_16x16x32_bf16 v[38:41], v[162:165], v[186:189], v[38:41]
	v_mfma_f32_16x16x32_bf16 v[22:25], v[158:161], v[190:193], v[22:25]
	v_mfma_f32_16x16x32_bf16 v[22:25], v[162:165], v[194:197], v[22:25]
	v_mfma_f32_16x16x32_bf16 v[18:21], v[166:169], v[190:193], v[18:21]
	v_mfma_f32_16x16x32_bf16 v[18:21], v[170:173], v[194:197], v[18:21]
	s_setprio 2
	s_barrier
	v_mfma_f32_16x16x32_bf16 v[2:5], v[166:169], v[198:201], v[2:5]
	v_mfma_f32_16x16x32_bf16 v[2:5], v[170:173], v[202:205], v[2:5]
	v_mfma_f32_16x16x32_bf16 v[6:9], v[158:161], v[198:201], v[6:9]
	v_mfma_f32_16x16x32_bf16 v[6:9], v[162:165], v[202:205], v[6:9]
	s_setprio 0
	s_nop 0
	s_add_i32 s59, 0, 0x18000
	s_add_i32 s60, 0, 0x1c000
	v_add_u32_e32 v154, s59, v140
	v_add_u32_e32 v170, s60, v140
	ds_read_b128 v[142:145], v154
	ds_read_b128 v[146:149], v154 offset:1024
	ds_read_b128 v[150:153], v154 offset:2048
	ds_read_b128 v[154:157], v154 offset:3072
	ds_read_b128 v[158:161], v170
	ds_read_b128 v[162:165], v170 offset:1024
	ds_read_b128 v[166:169], v170 offset:2048
	ds_read_b128 v[170:173], v170 offset:3072
	s_add_u32 s30, s30, 0xb0000
	s_addc_u32 s31, s31, 0
	s_mov_b32 m0, s52
	v_lshl_add_u64 v[222:223], s[30:31], 0, v[130:131]
	ds_read_b128 v[174:177], v141 offset:32768
	ds_read_b128 v[178:181], v141 offset:33792
	ds_read_b128 v[182:185], v141 offset:34816
	ds_read_b128 v[186:189], v141 offset:35840
	ds_read_b128 v[190:193], v141 offset:36864
	ds_read_b128 v[194:197], v141 offset:37888
	ds_read_b128 v[198:201], v141 offset:38912
	ds_read_b128 v[202:205], v141 offset:39936
	global_load_lds_dwordx4 v[222:223], off
	v_lshl_add_u64 v[222:223], s[30:31], 0, v[134:135]
	s_mov_b32 m0, s53
	s_nop 0
	global_load_lds_dwordx4 v[222:223], off
	s_waitcnt vmcnt(8)
	s_waitcnt lgkmcnt(0)
	s_barrier
	s_setprio 1
	v_mfma_f32_16x16x32_bf16 v[126:129], v[142:145], v[174:177], v[126:129]
	v_mfma_f32_16x16x32_bf16 v[126:129], v[146:149], v[178:181], v[126:129]
	v_mfma_f32_16x16x32_bf16 v[122:125], v[150:153], v[174:177], v[122:125]
	v_mfma_f32_16x16x32_bf16 v[122:125], v[154:157], v[178:181], v[122:125]
	v_mfma_f32_16x16x32_bf16 v[106:109], v[150:153], v[182:185], v[106:109]
	v_mfma_f32_16x16x32_bf16 v[106:109], v[154:157], v[186:189], v[106:109]
	v_mfma_f32_16x16x32_bf16 v[110:113], v[142:145], v[182:185], v[110:113]
	v_mfma_f32_16x16x32_bf16 v[110:113], v[146:149], v[186:189], v[110:113]
	v_mfma_f32_16x16x32_bf16 v[94:97], v[142:145], v[190:193], v[94:97]
	v_mfma_f32_16x16x32_bf16 v[94:97], v[146:149], v[194:197], v[94:97]
	v_mfma_f32_16x16x32_bf16 v[90:93], v[150:153], v[190:193], v[90:93]
	v_mfma_f32_16x16x32_bf16 v[90:93], v[154:157], v[194:197], v[90:93]
	v_mfma_f32_16x16x32_bf16 v[74:77], v[150:153], v[198:201], v[74:77]
	v_mfma_f32_16x16x32_bf16 v[74:77], v[154:157], v[202:205], v[74:77]
	v_mfma_f32_16x16x32_bf16 v[78:81], v[142:145], v[198:201], v[78:81]
	v_mfma_f32_16x16x32_bf16 v[78:81], v[146:149], v[202:205], v[78:81]
	v_mfma_f32_16x16x32_bf16 v[118:121], v[158:161], v[174:177], v[118:121]
	v_mfma_f32_16x16x32_bf16 v[118:121], v[162:165], v[178:181], v[118:121]
	v_mfma_f32_16x16x32_bf16 v[114:117], v[166:169], v[174:177], v[114:117]
	v_mfma_f32_16x16x32_bf16 v[114:117], v[170:173], v[178:181], v[114:117]
	v_mfma_f32_16x16x32_bf16 v[98:101], v[166:169], v[182:185], v[98:101]
	v_mfma_f32_16x16x32_bf16 v[98:101], v[170:173], v[186:189], v[98:101]
	v_mfma_f32_16x16x32_bf16 v[102:105], v[158:161], v[182:185], v[102:105]
	v_mfma_f32_16x16x32_bf16 v[102:105], v[162:165], v[186:189], v[102:105]
	v_mfma_f32_16x16x32_bf16 v[86:89], v[158:161], v[190:193], v[86:89]
	v_mfma_f32_16x16x32_bf16 v[86:89], v[162:165], v[194:197], v[86:89]
	v_mfma_f32_16x16x32_bf16 v[82:85], v[166:169], v[190:193], v[82:85]
	v_mfma_f32_16x16x32_bf16 v[82:85], v[170:173], v[194:197], v[82:85]
	s_setprio 2
	s_barrier
	v_mfma_f32_16x16x32_bf16 v[66:69], v[166:169], v[198:201], v[66:69]
	v_mfma_f32_16x16x32_bf16 v[66:69], v[170:173], v[202:205], v[66:69]
	v_mfma_f32_16x16x32_bf16 v[70:73], v[158:161], v[198:201], v[70:73]
	v_mfma_f32_16x16x32_bf16 v[70:73], v[162:165], v[202:205], v[70:73]
	s_setprio 0
	s_nop 0
	s_add_i32 s30, s59, s39
	v_lshl_add_u64 v[214:215], v[214:215], 0, s[24:25]
	s_mov_b32 m0, s30
	ds_read_b128 v[174:177], v141 offset:49152
	ds_read_b128 v[178:181], v141 offset:50176
	ds_read_b128 v[182:185], v141 offset:51200
	ds_read_b128 v[186:189], v141 offset:52224
	ds_read_b128 v[190:193], v141 offset:53248
	ds_read_b128 v[194:197], v141 offset:54272
	ds_read_b128 v[198:201], v141 offset:55296
	ds_read_b128 v[202:205], v141 offset:56320
	global_load_lds_dwordx4 v[214:215], off
	s_add_i32 m0, s30, 0x2000
	s_add_u32 s4, s4, 0xb0080
	v_lshl_add_u64 v[214:215], v[216:217], 0, s[24:25]
	s_addc_u32 s5, s5, 0
	s_add_i32 s30, s60, s39
	global_load_lds_dwordx4 v[214:215], off
	v_lshl_add_u64 v[214:215], s[4:5], 0, v[130:131]
	s_mov_b32 m0, s30
	s_nop 0
	global_load_lds_dwordx4 v[214:215], off
	v_lshl_add_u64 v[214:215], s[4:5], 0, v[134:135]
	s_add_i32 m0, s30, 0x2000
	s_nop 0
	global_load_lds_dwordx4 v[214:215], off
	v_lshl_add_u64 v[214:215], v[218:219], 0, s[24:25]
	s_mov_b32 m0, s54
	s_nop 0
	global_load_lds_dwordx4 v[214:215], off
	v_lshl_add_u64 v[214:215], v[220:221], 0, s[24:25]
	s_mov_b32 m0, s55
	s_nop 0
	global_load_lds_dwordx4 v[214:215], off
	s_waitcnt vmcnt(8)
	s_waitcnt lgkmcnt(0)
	s_barrier
	s_setprio 1
	v_mfma_f32_16x16x32_bf16 v[62:65], v[142:145], v[174:177], v[62:65]
	v_mfma_f32_16x16x32_bf16 v[62:65], v[146:149], v[178:181], v[62:65]
	v_mfma_f32_16x16x32_bf16 v[58:61], v[150:153], v[174:177], v[58:61]
	v_mfma_f32_16x16x32_bf16 v[58:61], v[154:157], v[178:181], v[58:61]
	v_mfma_f32_16x16x32_bf16 v[42:45], v[150:153], v[182:185], v[42:45]
	v_mfma_f32_16x16x32_bf16 v[42:45], v[154:157], v[186:189], v[42:45]
	v_mfma_f32_16x16x32_bf16 v[46:49], v[142:145], v[182:185], v[46:49]
	v_mfma_f32_16x16x32_bf16 v[46:49], v[146:149], v[186:189], v[46:49]
	v_mfma_f32_16x16x32_bf16 v[30:33], v[142:145], v[190:193], v[30:33]
	v_mfma_f32_16x16x32_bf16 v[30:33], v[146:149], v[194:197], v[30:33]
	v_mfma_f32_16x16x32_bf16 v[26:29], v[150:153], v[190:193], v[26:29]
	v_mfma_f32_16x16x32_bf16 v[26:29], v[154:157], v[194:197], v[26:29]
	v_mfma_f32_16x16x32_bf16 v[10:13], v[150:153], v[198:201], v[10:13]
	v_mfma_f32_16x16x32_bf16 v[10:13], v[154:157], v[202:205], v[10:13]
	v_mfma_f32_16x16x32_bf16 v[14:17], v[142:145], v[198:201], v[14:17]
	v_mfma_f32_16x16x32_bf16 v[14:17], v[146:149], v[202:205], v[14:17]
	v_mfma_f32_16x16x32_bf16 v[54:57], v[158:161], v[174:177], v[54:57]
	v_mfma_f32_16x16x32_bf16 v[54:57], v[162:165], v[178:181], v[54:57]
	v_mfma_f32_16x16x32_bf16 v[50:53], v[166:169], v[174:177], v[50:53]
	v_mfma_f32_16x16x32_bf16 v[50:53], v[170:173], v[178:181], v[50:53]
	v_mfma_f32_16x16x32_bf16 v[34:37], v[166:169], v[182:185], v[34:37]
	v_mfma_f32_16x16x32_bf16 v[34:37], v[170:173], v[186:189], v[34:37]
	v_mfma_f32_16x16x32_bf16 v[38:41], v[158:161], v[182:185], v[38:41]
	v_mfma_f32_16x16x32_bf16 v[38:41], v[162:165], v[186:189], v[38:41]
	v_mfma_f32_16x16x32_bf16 v[22:25], v[158:161], v[190:193], v[22:25]
	v_mfma_f32_16x16x32_bf16 v[22:25], v[162:165], v[194:197], v[22:25]
	v_mfma_f32_16x16x32_bf16 v[18:21], v[166:169], v[190:193], v[18:21]
	v_mfma_f32_16x16x32_bf16 v[18:21], v[170:173], v[194:197], v[18:21]
	s_setprio 2
	s_barrier
	v_mfma_f32_16x16x32_bf16 v[2:5], v[166:169], v[198:201], v[2:5]
	v_mfma_f32_16x16x32_bf16 v[2:5], v[170:173], v[202:205], v[2:5]
	v_mfma_f32_16x16x32_bf16 v[6:9], v[158:161], v[198:201], v[6:9]
	v_mfma_f32_16x16x32_bf16 v[6:9], v[162:165], v[202:205], v[6:9]
	s_setprio 0
	s_nop 0
	s_add_i32 s58, s58, 2
	s_add_u32 s56, s56, 0x100
	s_addc_u32 s57, s57, 0
	s_add_u32 s2, s2, 0x100
	s_addc_u32 s3, s3, 0
	v_lshl_add_u64 v[136:137], v[136:137], 0, s[28:29]
	s_cmp_lt_u32 s58, 42
	v_lshl_add_u64 v[138:139], v[138:139], 0, s[28:29]
	s_cbranch_scc1 .LBB0_1018
	s_nop 0
	s_cmpk_gt_u32 s36, 0xff
	s_cbranch_scc1 .LBB0_1021
	s_barrier
.LBB0_1021:
	s_lshl_b32 s2, s37, 8
	s_lshl_b32 s0, s38, 5
	v_add_u32_e32 v134, s2, v210
	s_or_b32 s0, s0, s41
	v_lshrrev_b32_e32 v130, 2, v211
	v_ashrrev_i32_e32 v135, 31, v134
	v_and_or_b32 v216, v130, 12, s0
	v_lshlrev_b64 v[136:137], 11, v[134:135]
	v_lshl_add_u64 v[136:137], s[64:65], 0, v[136:137]
	v_lshlrev_b32_e32 v130, 1, v216
	v_lshl_add_u64 v[136:137], v[136:137], 0, v[130:131]
	s_barrier
	global_load_dword v214, v131, s[70:71] sc1
	global_load_dword v215, v131, s[10:11] sc1
	global_load_dword v213, v131, s[12:13] sc1
	global_load_dwordx2 v[218:219], v[136:137], off
	global_load_dwordx2 v[220:221], v[136:137], off offset:32
	global_load_dwordx2 v[222:223], v[136:137], off offset:256
	global_load_dwordx2 v[224:225], v[136:137], off offset:288
	v_add_u32_e32 v136, 16, v134
	v_ashrrev_i32_e32 v137, 31, v136
	v_lshlrev_b64 v[138:139], 11, v[136:137]
	v_lshl_add_u64 v[138:139], s[64:65], 0, v[138:139]
	v_lshl_add_u64 v[138:139], v[138:139], 0, v[130:131]
	global_load_dwordx2 v[204:205], v[138:139], off
	global_load_dwordx2 v[202:203], v[138:139], off offset:32
	global_load_dwordx2 v[200:201], v[138:139], off offset:256
	global_load_dwordx2 v[198:199], v[138:139], off offset:288
	v_add_u32_e32 v138, 32, v134
	v_ashrrev_i32_e32 v139, 31, v138
	v_lshlrev_b64 v[140:141], 11, v[138:139]
	v_lshl_add_u64 v[140:141], s[64:65], 0, v[140:141]
	v_lshl_add_u64 v[140:141], v[140:141], 0, v[130:131]
	global_load_dwordx2 v[196:197], v[140:141], off
	global_load_dwordx2 v[194:195], v[140:141], off offset:32
	global_load_dwordx2 v[192:193], v[140:141], off offset:256
	global_load_dwordx2 v[190:191], v[140:141], off offset:288
	v_add_u32_e32 v140, 48, v134
	v_ashrrev_i32_e32 v141, 31, v140
	v_lshlrev_b64 v[142:143], 11, v[140:141]
	v_lshl_add_u64 v[142:143], s[64:65], 0, v[142:143]
	v_lshl_add_u64 v[142:143], v[142:143], 0, v[130:131]
	global_load_dwordx2 v[188:189], v[142:143], off
	global_load_dwordx2 v[186:187], v[142:143], off offset:32
	global_load_dwordx2 v[184:185], v[142:143], off offset:256
	global_load_dwordx2 v[182:183], v[142:143], off offset:288
	v_add_u32_e32 v142, 0x80, v134
	v_ashrrev_i32_e32 v143, 31, v142
	v_lshlrev_b64 v[144:145], 11, v[142:143]
	v_lshl_add_u64 v[144:145], s[64:65], 0, v[144:145]
	v_lshl_add_u64 v[144:145], v[144:145], 0, v[130:131]
	global_load_dwordx2 v[180:181], v[144:145], off
	global_load_dwordx2 v[178:179], v[144:145], off offset:32
	global_load_dwordx2 v[176:177], v[144:145], off offset:256
	global_load_dwordx2 v[174:175], v[144:145], off offset:288
	v_add_u32_e32 v144, 0x90, v134
	v_ashrrev_i32_e32 v145, 31, v144
	v_lshlrev_b64 v[146:147], 11, v[144:145]
	v_lshl_add_u64 v[146:147], s[64:65], 0, v[146:147]
	v_lshl_add_u64 v[146:147], v[146:147], 0, v[130:131]
	global_load_dwordx2 v[172:173], v[146:147], off
	global_load_dwordx2 v[170:171], v[146:147], off offset:32
	global_load_dwordx2 v[168:169], v[146:147], off offset:256
	global_load_dwordx2 v[166:167], v[146:147], off offset:288
	v_add_u32_e32 v146, 0xa0, v134
	v_ashrrev_i32_e32 v147, 31, v146
	v_lshlrev_b64 v[148:149], 11, v[146:147]
	v_lshl_add_u64 v[148:149], s[64:65], 0, v[148:149]
	v_lshl_add_u64 v[148:149], v[148:149], 0, v[130:131]
	global_load_dwordx2 v[164:165], v[148:149], off
	global_load_dwordx2 v[162:163], v[148:149], off offset:32
	global_load_dwordx2 v[160:161], v[148:149], off offset:256
	global_load_dwordx2 v[158:159], v[148:149], off offset:288
	v_add_u32_e32 v148, 0xb0, v134
	v_ashrrev_i32_e32 v149, 31, v148
	v_lshlrev_b64 v[150:151], 11, v[148:149]
	v_lshl_add_u64 v[150:151], s[64:65], 0, v[150:151]
	v_lshl_add_u64 v[150:151], v[150:151], 0, v[130:131]
	global_load_dwordx2 v[156:157], v[150:151], off
	global_load_dwordx2 v[154:155], v[150:151], off offset:32
	global_load_dwordx2 v[152:153], v[150:151], off offset:256
	s_nop 0
	global_load_dwordx2 v[150:151], v[150:151], off offset:288
	v_and_b32_e32 v217, 64, v1
	v_xor_b32_e32 v130, 16, v1
	s_lshl_b32 s0, s38, 2
	s_add_i32 s3, s0, 0x20000
	s_waitcnt vmcnt(31)
	v_lshlrev_b32_e32 v226, 16, v218
	v_and_b32_e32 v227, 0xffff0000, v218
	v_lshlrev_b32_e32 v218, 16, v219
	v_and_b32_e32 v219, 0xffff0000, v219
	v_pk_add_f32 v[128:129], v[128:129], v[218:219]
	s_waitcnt vmcnt(30)
	v_lshlrev_b32_e32 v218, 16, v220
	v_and_b32_e32 v219, 0xffff0000, v220
	v_pk_add_f32 v[122:123], v[122:123], v[218:219]
	s_waitcnt vmcnt(29)
	v_lshlrev_b32_e32 v218, 16, v222
	v_and_b32_e32 v219, 0xffff0000, v222
	v_pk_add_f32 v[118:119], v[118:119], v[218:219]
	s_waitcnt vmcnt(28)
	v_lshlrev_b32_e32 v218, 16, v224
	v_and_b32_e32 v219, 0xffff0000, v224
	v_pk_add_f32 v[114:115], v[114:115], v[218:219]
	v_add_u32_e32 v218, 64, v217
	v_cmp_lt_i32_e32 vcc, v130, v218
	v_pk_add_f32 v[126:127], v[126:127], v[226:227]
	v_lshlrev_b32_e32 v220, 16, v221
	v_and_b32_e32 v221, 0xffff0000, v221
	v_cndmask_b32_e32 v130, v1, v130, vcc
	v_pk_add_f32 v[124:125], v[124:125], v[220:221]
	v_lshlrev_b32_e32 v220, 16, v223
	v_and_b32_e32 v221, 0xffff0000, v223
	v_lshlrev_b32_e32 v217, 2, v130
	v_mul_f32_e32 v130, v127, v127
	v_mul_f32_e32 v219, v129, v129
	v_pk_add_f32 v[120:121], v[120:121], v[220:221]
	v_lshlrev_b32_e32 v220, 16, v225
	v_and_b32_e32 v221, 0xffff0000, v225
	v_fmac_f32_e32 v130, v126, v126
	v_fmac_f32_e32 v219, v128, v128
	v_pk_add_f32 v[116:117], v[116:117], v[220:221]
	v_add_f32_e32 v130, v130, v219
	v_mul_f32_e32 v219, v123, v123
	v_mul_f32_e32 v220, v125, v125
	v_fmac_f32_e32 v219, v122, v122
	v_fmac_f32_e32 v220, v124, v124
	v_add_f32_e32 v219, v219, v220
	v_add_f32_e32 v130, v130, v219
	v_mul_f32_e32 v219, v119, v119
	v_mul_f32_e32 v220, v121, v121
	v_fmac_f32_e32 v219, v118, v118
	v_fmac_f32_e32 v220, v120, v120
	v_add_f32_e32 v219, v219, v220
	v_add_f32_e32 v130, v130, v219
	v_mul_f32_e32 v219, v115, v115
	v_mul_f32_e32 v220, v117, v117
	v_fmac_f32_e32 v219, v114, v114
	v_fmac_f32_e32 v220, v116, v116
	v_add_f32_e32 v219, v219, v220
	v_add_f32_e32 v130, v130, v219
	ds_bpermute_b32 v219, v217, v130
	v_xor_b32_e32 v220, 32, v1
	v_cmp_lt_i32_e32 vcc, v220, v218
	s_waitcnt lgkmcnt(0)
	v_add_f32_e32 v219, v130, v219
	v_cndmask_b32_e32 v218, v1, v220, vcc
	v_lshlrev_b32_e32 v218, 2, v218
	ds_bpermute_b32 v220, v218, v219
	v_and_b32_e32 v130, 63, v211
	v_cmp_gt_u32_e32 vcc, 16, v130
	s_and_saveexec_b64 s[0:1], vcc
	s_cbranch_execz .LBB0_1023
	s_lshl_b32 s4, s35, 10
	s_add_i32 s4, s3, s4
	v_lshl_add_u32 v221, v212, 4, s4
	s_waitcnt lgkmcnt(0)
	v_add_f32_e32 v219, v219, v220
	ds_write_b32 v221, v219

.LBB0_1037:
	s_or_b64 exec, exec, s[0:1]
	v_and_b32_e32 v2, 31, v211
	s_waitcnt lgkmcnt(0)
	s_barrier
	v_lshl_or_b32 v4, s34, 5, v2
	v_add_u32_e32 v2, s2, v4
	v_cmp_gt_u32_e64 s[0:1], 32, v130
	s_waitcnt lgkmcnt(0)
	v_ashrrev_i32_e32 v3, 31, v2
	s_and_saveexec_b64 s[2:3], s[0:1]
	s_cbranch_execz .LBB0_1039
	v_lshlrev_b32_e32 v5, 4, v4
	v_add_u32_e32 v5, 0x20000, v5
	ds_read_b128 v[6:9], v5
	v_lshlrev_b64 v[10:11], 5, v[2:3]
	s_waitcnt lgkmcnt(0)
	v_mov_b32_e32 v12, v7
	v_mov_b32_e32 v13, v8
	v_mov_b32_e32 v7, v9
	v_pk_add_f32 v[6:7], v[12:13], v[6:7]
	v_lshl_add_u64 v[8:9], s[20:21], 0, v[10:11]
	v_pk_add_f32 v[6:7], v[6:7], v[6:7] op_sel:[0,1] op_sel_hi:[1,0]
	s_nop 0
	v_mov_b32_e32 v7, v131
	global_store_dwordx2 v[8:9], v[6:7], off sc1

.LBB0_1056:
	s_waitcnt vmcnt(0)
	buffer_inv sc1
	s_and_b64 exec, exec, s[2:3]
	v_cndmask_b32_e64 v5, 0, 1, s[30:31]
	v_mov_b32_e32 v6, 0x22800
	ds_write_b32 v6, v5

.LBB0_1059:
	s_waitcnt vmcnt(0) lgkmcnt(0)
	s_barrier
	v_mov_b32_e32 v168, 0x22800
	ds_read_b32 v168, v168
	s_and_saveexec_b64 s[2:3], s[0:1]
	s_cbranch_execz .LBB0_1012
	v_lshlrev_b64 v[2:3], 5, v[2:3]
	v_lshl_add_u64 v[2:3], s[6:7], 0, v[2:3]
	global_load_dwordx2 v[6:7], v[2:3], off sc1
	global_load_dwordx2 v[8:9], v[2:3], off offset:8 sc1
	global_load_dwordx2 v[10:11], v[2:3], off offset:16 sc1
	s_nop 0
	global_load_dwordx2 v[2:3], v[2:3], off offset:24 sc1
	s_waitcnt vmcnt(0)
	v_add_f32_e32 v3, 0, v6
	v_add_f32_e32 v3, v3, v8
	v_add_f32_e32 v3, v3, v10
	v_add_f32_e32 v2, v3, v2
	v_fmamk_f32 v2, v2, 0x3a800000, v207
	v_mul_f32_e32 v3, 0x4f800000, v2
	v_cmp_gt_f32_e32 vcc, s48, v2
	s_nop 1
	v_cndmask_b32_e32 v2, v2, v3, vcc
	v_sqrt_f32_e32 v3, v2
	s_nop 0
	v_add_u32_e32 v5, -1, v3
	v_add_u32_e32 v6, 1, v3
	v_fma_f32 v7, -v5, v3, v2
	v_fma_f32 v8, -v6, v3, v2
	v_cmp_ge_f32_e64 s[0:1], 0, v7
	s_nop 1
	v_cndmask_b32_e64 v3, v3, v5, s[0:1]
	v_cmp_lt_f32_e64 s[0:1], 0, v8
	s_nop 1
	v_cndmask_b32_e64 v3, v3, v6, s[0:1]
	v_mul_f32_e32 v5, 0x37800000, v3
	v_cndmask_b32_e32 v3, v3, v5, vcc
	v_cmp_class_f32_e32 vcc, v2, v208
	s_nop 1
	v_cndmask_b32_e32 v2, v3, v2, vcc
	v_div_scale_f32 v3, s[0:1], v2, v2, 1.0
	v_rcp_f32_e32 v5, v3
	v_div_scale_f32 v6, vcc, 1.0, v2, 1.0
	v_fma_f32 v7, -v3, v5, 1.0
	v_fmac_f32_e32 v5, v7, v5
	v_mul_f32_e32 v7, v6, v5
	v_fma_f32 v8, -v3, v7, v6
	v_fmac_f32_e32 v7, v8, v5
	v_fma_f32 v3, -v3, v7, v6
	v_div_fmas_f32 v3, v3, v5, v7
	v_div_fixup_f32 v2, v3, v2, 1.0
	v_lshlrev_b32_e32 v3, 2, v4
	v_add_u32_e32 v3, 0x20000, v3
	ds_write_b32 v3, v2 offset:8192
	s_branch .LBB0_1012
